# v28 + P6 LN-epilogue pass 1: bias/gate vector loads hoisted out of the 8 steps into the prologue (v216-247), per-step waits now only on x
# speedup vs baseline: 1.0081x; 1.0071x over previous
;     __device__ __forceinline__ void fused(f32x4 (&acc)[2][2][4][2], const Unit& u, int wr, int wc, int fr, int fq, PG8_LAS unsigned char* lds, int wid, int lane) const {
;     ...
;         for (int m = 0; m < 4; ++m) xc[m] = __builtin_nontemporal_load((const f32x4*)(xp + (size_t)(m * 16) * D));
; #pragma unroll
;         for (int g = 0; g < 8; ++g) { const int bj = g >> 2, n = (g >> 1) & 1, ai = g & 1; const int c = col0 + bj * 128 + n * 16;
;             if (g < 7) { const int g1 = g + 1, bj1 = g1 >> 2, n1 = (g1 >> 1) & 1, ai1 = g1 & 1;
; #pragma unroll
;                 for (int m = 0; m < 4; ++m) xn[m] = __builtin_nontemporal_load((const f32x4*)(xp + (size_t)(ai1 * 128 + m * 16) * D + bj1 * 128 + n1 * 16)); }
;             const f32x4 gv = *(const f32x4*)(gate + c), bv = *(const f32x4*)(bo + c);
;             asm volatile("" ::: "memory");
; #pragma unroll
;             for (int m = 0; m < 4; ++m) acc[ai][bj][m][n] = xc[m] * ALPHA + gv * (acc[ai][bj][m][n] + bv);
;             asm volatile("" : "+v"(acc[ai][bj][0][n]), "+v"(acc[ai][bj][1][n]), "+v"(acc[ai][bj][2][n]), "+v"(acc[ai][bj][3][n]));
;             asm volatile("" ::: "memory");
; #pragma unroll
;             for (int m = 0; m < 4; ++m) xc[m] = xn[m]; }
.LBB0_496:
	s_lshl_b32 s0, s39, 5
	s_lshl_b32 s1, s4, 8
	s_or_b32 s0, s1, s0
	v_lshrrev_b32_e32 v128, 2, v174
	v_and_or_b32 v166, v128, 12, s0
	s_lshl_b32 s6, s38, 8
	v_mov_b32_e32 v128, v149
	s_barrier
	v_add_u32_e32 v152, s6, v153
	v_add_u32_e32 v128, v128, v152
	v_ashrrev_i32_e32 v129, 31, v128
	v_lshlrev_b64 v[128:129], 12, v[128:129]
	v_ashrrev_i32_e32 v167, 31, v166
	s_ashr_i32 s0, s38, 3
	v_lshlrev_b64 v[154:155], 2, v[166:167]
	v_lshl_add_u64 v[128:129], s[76:77], 0, v[128:129]
	s_mul_hi_i32 s1, s0, 0x3000
	s_mulk_i32 s0, 0x3000
	v_lshl_add_u64 v[140:141], v[128:129], 0, v[154:155]
	s_add_u32 s0, s96, s0
	v_add_co_u32_e32 v136, vcc, s51, v140
	s_addc_u32 s1, s97, s1
	v_readlane_b32 s60, v250, 0
	v_addc_co_u32_e32 v137, vcc, 0, v141, vcc
	v_readlane_b32 s64, v250, 4
	v_readlane_b32 s65, v250, 5
	s_add_u32 s0, s0, 0x2000
	v_add_co_u32_e32 v128, vcc, s52, v140
	v_lshl_add_u64 v[156:157], s[64:65], 0, v[154:155]
	s_addc_u32 s1, s1, 0
	v_addc_co_u32_e32 v129, vcc, 0, v141, vcc
	global_load_dwordx4 v[216:219], v[156:157], off
	global_load_dwordx4 v[220:223], v[156:157], off offset:64
	global_load_dwordx4 v[224:227], v[156:157], off offset:512
	global_load_dwordx4 v[228:231], v[156:157], off offset:576
	v_lshl_add_u64 v[138:139], s[0:1], 0, v[154:155]
	v_add_co_u32_e32 v130, vcc, s53, v140
	global_load_dwordx4 v[232:235], v[138:139], off
	global_load_dwordx4 v[236:239], v[138:139], off offset:64
	global_load_dwordx4 v[240:243], v[138:139], off offset:512
	global_load_dwordx4 v[244:247], v[138:139], off offset:576
	s_nop 0
	v_addc_co_u32_e32 v131, vcc, 0, v141, vcc
	global_load_dwordx4 v[180:183], v[140:141], off nt
	global_load_dwordx4 v[184:187], v[136:137], off nt
	global_load_dwordx4 v[188:191], v[128:129], off nt
	global_load_dwordx4 v[192:195], v[130:131], off nt
	v_add_co_u32_e32 v158, vcc, s54, v140
	v_xor_b32_e32 v148, 16, v172
	s_nop 0
	v_addc_co_u32_e32 v159, vcc, 0, v141, vcc
	v_add_co_u32_e32 v160, vcc, s55, v140
	v_readlane_b32 s61, v250, 1
	s_nop 0
	v_addc_co_u32_e32 v161, vcc, 0, v141, vcc
	v_add_co_u32_e32 v162, vcc, s56, v140
	v_readlane_b32 s62, v250, 2
	s_nop 0
	v_addc_co_u32_e32 v163, vcc, 0, v141, vcc
	v_add_co_u32_e32 v164, vcc, s57, v140
	v_readlane_b32 s63, v250, 3
	s_nop 0
	v_addc_co_u32_e32 v165, vcc, 0, v141, vcc
	global_load_dwordx4 v[196:199], v[158:159], off nt
	global_load_dwordx4 v[200:203], v[160:161], off nt
	global_load_dwordx4 v[204:207], v[162:163], off nt
	global_load_dwordx4 v[208:211], v[164:165], off nt
	v_readlane_b32 s66, v250, 6
	v_readlane_b32 s67, v250, 7
	s_waitcnt vmcnt(4)
	v_pk_add_f32 v[82:83], v[82:83], v[218:219]
	v_pk_add_f32 v[80:81], v[80:81], v[216:217]
	v_pk_add_f32 v[78:79], v[78:79], v[218:219]
	v_pk_add_f32 v[76:77], v[76:77], v[216:217]
	v_pk_add_f32 v[66:67], v[66:67], v[218:219]
	v_pk_add_f32 v[64:65], v[64:65], v[216:217]
	v_pk_add_f32 v[62:63], v[62:63], v[218:219]
	v_pk_add_f32 v[60:61], v[60:61], v[216:217]
	v_pk_mul_f32 v[82:83], v[234:235], v[82:83]
	v_pk_mul_f32 v[80:81], v[232:233], v[80:81]
	v_pk_mul_f32 v[78:79], v[234:235], v[78:79]
	v_pk_mul_f32 v[76:77], v[232:233], v[76:77]
	v_pk_mul_f32 v[66:67], v[234:235], v[66:67]
	v_pk_mul_f32 v[64:65], v[232:233], v[64:65]
	v_pk_mul_f32 v[132:133], v[234:235], v[62:63]
	v_pk_mul_f32 v[134:135], v[232:233], v[60:61]
	v_pk_fma_f32 v[82:83], v[182:183], s[34:35], v[82:83] op_sel_hi:[1,0,1]
	v_pk_fma_f32 v[80:81], v[180:181], s[34:35], v[80:81] op_sel_hi:[1,0,1]
	v_pk_fma_f32 v[78:79], v[186:187], s[34:35], v[78:79] op_sel_hi:[1,0,1]
	v_pk_fma_f32 v[76:77], v[184:185], s[34:35], v[76:77] op_sel_hi:[1,0,1]
	v_pk_fma_f32 v[62:63], v[190:191], s[34:35], v[66:67] op_sel_hi:[1,0,1]
	v_pk_fma_f32 v[60:61], v[188:189], s[34:35], v[64:65] op_sel_hi:[1,0,1]
	v_pk_fma_f32 v[66:67], v[194:195], s[34:35], v[132:133] op_sel_hi:[1,0,1]
	v_pk_fma_f32 v[64:65], v[192:193], s[34:35], v[134:135] op_sel_hi:[1,0,1]
	s_nop 0
	global_load_dwordx4 v[180:183], v[130:131], off offset:64 nt
	global_load_dwordx4 v[184:187], v[128:129], off offset:64 nt
	global_load_dwordx4 v[188:191], v[136:137], off offset:64 nt
	global_load_dwordx4 v[192:195], v[140:141], off offset:64 nt
	v_or_b32_e32 v138, 16, v166
	v_ashrrev_i32_e32 v139, 31, v138
	v_lshl_add_u64 v[138:139], v[138:139], 2, s[0:1]
	s_waitcnt vmcnt(4)
	v_pk_add_f32 v[94:95], v[94:95], v[218:219]
	v_pk_add_f32 v[92:93], v[92:93], v[216:217]
	v_pk_add_f32 v[90:91], v[90:91], v[218:219]
	v_pk_add_f32 v[88:89], v[88:89], v[216:217]
	v_pk_add_f32 v[46:47], v[46:47], v[218:219]
	v_pk_add_f32 v[44:45], v[44:45], v[216:217]
	v_pk_add_f32 v[30:31], v[30:31], v[218:219]
	v_pk_add_f32 v[28:29], v[28:29], v[216:217]
	s_waitcnt vmcnt(4)
	v_pk_mul_f32 v[94:95], v[234:235], v[94:95]
	v_pk_mul_f32 v[92:93], v[232:233], v[92:93]
	v_pk_mul_f32 v[90:91], v[234:235], v[90:91]
	v_pk_mul_f32 v[88:89], v[232:233], v[88:89]
	v_pk_mul_f32 v[46:47], v[234:235], v[46:47]
	v_pk_mul_f32 v[44:45], v[232:233], v[44:45]
	v_pk_mul_f32 v[30:31], v[234:235], v[30:31]
	v_pk_mul_f32 v[28:29], v[232:233], v[28:29]
	v_pk_fma_f32 v[94:95], v[210:211], s[34:35], v[94:95] op_sel_hi:[1,0,1]
	v_pk_fma_f32 v[92:93], v[208:209], s[34:35], v[92:93] op_sel_hi:[1,0,1]
	v_pk_fma_f32 v[90:91], v[206:207], s[34:35], v[90:91] op_sel_hi:[1,0,1]
	v_pk_fma_f32 v[88:89], v[204:205], s[34:35], v[88:89] op_sel_hi:[1,0,1]
	v_pk_fma_f32 v[46:47], v[202:203], s[34:35], v[46:47] op_sel_hi:[1,0,1]
	v_pk_fma_f32 v[44:45], v[200:201], s[34:35], v[44:45] op_sel_hi:[1,0,1]
	v_pk_fma_f32 v[30:31], v[198:199], s[34:35], v[30:31] op_sel_hi:[1,0,1]
	v_pk_fma_f32 v[28:29], v[196:197], s[34:35], v[28:29] op_sel_hi:[1,0,1]
	s_nop 0
	global_load_dwordx4 v[196:199], v[158:159], off offset:64 nt
	global_load_dwordx4 v[200:203], v[160:161], off offset:64 nt
	global_load_dwordx4 v[204:207], v[162:163], off offset:64 nt
	global_load_dwordx4 v[208:211], v[164:165], off offset:64 nt
	s_waitcnt vmcnt(4)
;     __device__ __forceinline__ void fused(f32x4 (&acc)[2][2][4][2], const Unit& u, int wr, int wc, int fr, int fq, PG8_LAS unsigned char* lds, int wid, int lane) const {
;     ...
;         for (int g = 0; g < 8; ++g) { const int bj = g >> 2, n = (g >> 1) & 1, ai = g & 1; const int c = col0 + bj * 128 + n * 16;
;             if (g < 7) { const int g1 = g + 1, bj1 = g1 >> 2, n1 = (g1 >> 1) & 1, ai1 = g1 & 1;
; #pragma unroll
;                 for (int m = 0; m < 4; ++m) xn[m] = __builtin_nontemporal_load((const f32x4*)(xp + (size_t)(ai1 * 128 + m * 16) * D + bj1 * 128 + n1 * 16)); }
;             const f32x4 gv = *(const f32x4*)(gate + c), bv = *(const f32x4*)(bo + c);
;             asm volatile("" ::: "memory");
; #pragma unroll
;             for (int m = 0; m < 4; ++m) acc[ai][bj][m][n] = xc[m] * ALPHA + gv * (acc[ai][bj][m][n] + bv);
;             asm volatile("" : "+v"(acc[ai][bj][0][n]), "+v"(acc[ai][bj][1][n]), "+v"(acc[ai][bj][2][n]), "+v"(acc[ai][bj][3][n]));
;             asm volatile("" ::: "memory");
; #pragma unroll
;             for (int m = 0; m < 4; ++m) xc[m] = xn[m]; }
	v_pk_add_f32 v[86:87], v[86:87], v[222:223]
	v_pk_add_f32 v[84:85], v[84:85], v[220:221]
	v_pk_add_f32 v[54:55], v[54:55], v[222:223]
	v_pk_add_f32 v[52:53], v[52:53], v[220:221]
	v_pk_add_f32 v[34:35], v[34:35], v[222:223]
	v_pk_add_f32 v[32:33], v[32:33], v[220:221]
	v_pk_add_f32 v[18:19], v[18:19], v[222:223]
	v_pk_add_f32 v[16:17], v[16:17], v[220:221]
	s_waitcnt vmcnt(4)
	v_pk_mul_f32 v[86:87], v[238:239], v[86:87]
	v_pk_mul_f32 v[84:85], v[236:237], v[84:85]
	v_pk_mul_f32 v[54:55], v[238:239], v[54:55]
	v_pk_mul_f32 v[52:53], v[236:237], v[52:53]
	v_pk_mul_f32 v[34:35], v[238:239], v[34:35]
	v_pk_mul_f32 v[32:33], v[236:237], v[32:33]
	v_pk_mul_f32 v[18:19], v[238:239], v[18:19]
	v_pk_mul_f32 v[16:17], v[236:237], v[16:17]
	v_pk_fma_f32 v[86:87], v[194:195], s[34:35], v[86:87] op_sel_hi:[1,0,1]
	v_pk_fma_f32 v[84:85], v[192:193], s[34:35], v[84:85] op_sel_hi:[1,0,1]
	v_pk_fma_f32 v[54:55], v[190:191], s[34:35], v[54:55] op_sel_hi:[1,0,1]
	v_pk_fma_f32 v[52:53], v[188:189], s[34:35], v[52:53] op_sel_hi:[1,0,1]
	v_pk_fma_f32 v[34:35], v[186:187], s[34:35], v[34:35] op_sel_hi:[1,0,1]
	v_pk_fma_f32 v[32:33], v[184:185], s[34:35], v[32:33] op_sel_hi:[1,0,1]
	v_pk_fma_f32 v[18:19], v[182:183], s[34:35], v[18:19] op_sel_hi:[1,0,1]
	v_pk_fma_f32 v[16:17], v[180:181], s[34:35], v[16:17] op_sel_hi:[1,0,1]
	s_nop 0
	global_load_dwordx4 v[180:183], v[130:131], off offset:512 nt
	global_load_dwordx4 v[184:187], v[128:129], off offset:512 nt
	global_load_dwordx4 v[188:191], v[136:137], off offset:512 nt
	global_load_dwordx4 v[192:195], v[140:141], off offset:512 nt
	v_or_b32_e32 v138, 0x80, v166
	v_ashrrev_i32_e32 v139, 31, v138
	v_lshl_add_u64 v[138:139], v[138:139], 2, s[0:1]
	v_or_b32_e32 v166, 0x90, v166
	v_ashrrev_i32_e32 v167, 31, v166
	s_waitcnt vmcnt(4)
	v_pk_add_f32 v[70:71], v[70:71], v[222:223]
	v_pk_add_f32 v[68:69], v[68:69], v[220:221]
	v_pk_add_f32 v[50:51], v[50:51], v[222:223]
	v_pk_add_f32 v[48:49], v[48:49], v[220:221]
	v_pk_add_f32 v[26:27], v[26:27], v[222:223]
	v_pk_add_f32 v[24:25], v[24:25], v[220:221]
	v_pk_add_f32 v[10:11], v[10:11], v[222:223]
	v_pk_add_f32 v[8:9], v[8:9], v[220:221]
	s_waitcnt vmcnt(4)
	v_pk_mul_f32 v[70:71], v[238:239], v[70:71]
	v_pk_mul_f32 v[68:69], v[236:237], v[68:69]
	v_pk_mul_f32 v[50:51], v[238:239], v[50:51]
	v_pk_mul_f32 v[48:49], v[236:237], v[48:49]
	v_pk_mul_f32 v[26:27], v[238:239], v[26:27]
	v_pk_mul_f32 v[24:25], v[236:237], v[24:25]
	v_pk_mul_f32 v[10:11], v[238:239], v[10:11]
	v_pk_mul_f32 v[8:9], v[236:237], v[8:9]
	v_pk_fma_f32 v[70:71], v[210:211], s[34:35], v[70:71] op_sel_hi:[1,0,1]
	v_pk_fma_f32 v[68:69], v[208:209], s[34:35], v[68:69] op_sel_hi:[1,0,1]
	v_pk_fma_f32 v[50:51], v[206:207], s[34:35], v[50:51] op_sel_hi:[1,0,1]
	v_pk_fma_f32 v[48:49], v[204:205], s[34:35], v[48:49] op_sel_hi:[1,0,1]
	v_pk_fma_f32 v[26:27], v[202:203], s[34:35], v[26:27] op_sel_hi:[1,0,1]
	v_pk_fma_f32 v[24:25], v[200:201], s[34:35], v[24:25] op_sel_hi:[1,0,1]
	v_pk_fma_f32 v[10:11], v[198:199], s[34:35], v[10:11] op_sel_hi:[1,0,1]
	v_pk_fma_f32 v[8:9], v[196:197], s[34:35], v[8:9] op_sel_hi:[1,0,1]
	s_nop 0
	global_load_dwordx4 v[196:199], v[158:159], off offset:512 nt
	global_load_dwordx4 v[200:203], v[160:161], off offset:512 nt
	global_load_dwordx4 v[204:207], v[162:163], off offset:512 nt
	global_load_dwordx4 v[208:211], v[164:165], off offset:512 nt
	s_waitcnt vmcnt(4)
	v_pk_add_f32 v[74:75], v[74:75], v[226:227]
	v_pk_add_f32 v[72:73], v[72:73], v[224:225]
	v_pk_add_f32 v[42:43], v[42:43], v[226:227]
	v_pk_add_f32 v[40:41], v[40:41], v[224:225]
	v_pk_add_f32 v[22:23], v[22:23], v[226:227]
	v_pk_add_f32 v[20:21], v[20:21], v[224:225]
	v_pk_add_f32 v[6:7], v[6:7], v[226:227]
	v_pk_add_f32 v[4:5], v[4:5], v[224:225]
	s_waitcnt vmcnt(4)
	v_pk_mul_f32 v[74:75], v[242:243], v[74:75]
	v_pk_mul_f32 v[72:73], v[240:241], v[72:73]
	v_pk_mul_f32 v[42:43], v[242:243], v[42:43]
	v_pk_mul_f32 v[40:41], v[240:241], v[40:41]
	v_pk_mul_f32 v[22:23], v[242:243], v[22:23]
	v_pk_mul_f32 v[20:21], v[240:241], v[20:21]
	v_pk_mul_f32 v[6:7], v[242:243], v[6:7]
	v_pk_mul_f32 v[4:5], v[240:241], v[4:5]
	v_pk_fma_f32 v[74:75], v[194:195], s[34:35], v[74:75] op_sel_hi:[1,0,1]
	v_pk_fma_f32 v[72:73], v[192:193], s[34:35], v[72:73] op_sel_hi:[1,0,1]
	v_pk_fma_f32 v[42:43], v[190:191], s[34:35], v[42:43] op_sel_hi:[1,0,1]
	v_pk_fma_f32 v[40:41], v[188:189], s[34:35], v[40:41] op_sel_hi:[1,0,1]
	v_pk_fma_f32 v[22:23], v[186:187], s[34:35], v[22:23] op_sel_hi:[1,0,1]
	v_pk_fma_f32 v[20:21], v[184:185], s[34:35], v[20:21] op_sel_hi:[1,0,1]
	v_pk_fma_f32 v[6:7], v[182:183], s[34:35], v[6:7] op_sel_hi:[1,0,1]
	v_pk_fma_f32 v[4:5], v[180:181], s[34:35], v[4:5] op_sel_hi:[1,0,1]
	v_lshl_add_u64 v[192:193], v[166:167], 2, s[0:1]
	global_load_dwordx4 v[132:135], v[128:129], off offset:576 nt
	s_nop 0
	global_load_dwordx4 v[128:131], v[130:131], off offset:576 nt
	s_nop 0
	global_load_dwordx4 v[136:139], v[136:137], off offset:576 nt
	s_nop 0
	global_load_dwordx4 v[140:143], v[140:141], off offset:576 nt
	v_and_b32_e32 v166, 64, v172
	v_mov_b32_e32 v194, v81
	v_mov_b32_e32 v195, v82
	s_lshl_b32 s0, s39, 3
	s_add_i32 s7, s0, 0
	s_waitcnt vmcnt(4)
	v_pk_add_f32 v[58:59], v[58:59], v[226:227]
	v_pk_add_f32 v[56:57], v[56:57], v[224:225]
	v_pk_add_f32 v[38:39], v[38:39], v[226:227]
	v_pk_add_f32 v[36:37], v[36:37], v[224:225]
	v_pk_add_f32 v[14:15], v[14:15], v[226:227]
	v_pk_add_f32 v[12:13], v[12:13], v[224:225]
	v_pk_add_f32 v[2:3], v[2:3], v[226:227]
	v_pk_add_f32 v[0:1], v[0:1], v[224:225]
	s_waitcnt vmcnt(4)
;     __device__ __forceinline__ bool run(const f32x4 (&v)[2][2][4][2], const Unit& u, int wr, int wc, int fr, int fq, PG8_LAS unsigned char* lds, int wid, int lane) const {
;     ...
;                     for (int n = 0; n < 2; ++n) { const f32x4 x = v[ai][bj][m][n]; s += (x[0] + x[1]) + (x[2] + x[3]); }
;                 s += __shfl_xor(s, 16); s += __shfl_xor(s, 32);
;     __device__ __forceinline__ void fused(f32x4 (&acc)[2][2][4][2], const Unit& u, int wr, int wc, int fr, int fq, PG8_LAS unsigned char* lds, int wid, int lane) const {
;     ...
;         for (int g = 0; g < 8; ++g) { const int bj = g >> 2, n = (g >> 1) & 1, ai = g & 1; const int c = col0 + bj * 128 + n * 16;
;             if (g < 7) { const int g1 = g + 1, bj1 = g1 >> 2, n1 = (g1 >> 1) & 1, ai1 = g1 & 1;
; #pragma unroll
;                 for (int m = 0; m < 4; ++m) xn[m] = __builtin_nontemporal_load((const f32x4*)(xp + (size_t)(ai1 * 128 + m * 16) * D + bj1 * 128 + n1 * 16)); }
;             const f32x4 gv = *(const f32x4*)(gate + c), bv = *(const f32x4*)(bo + c);
;             asm volatile("" ::: "memory");
; #pragma unroll
;             for (int m = 0; m < 4; ++m) acc[ai][bj][m][n] = xc[m] * ALPHA + gv * (acc[ai][bj][m][n] + bv);
;             asm volatile("" : "+v"(acc[ai][bj][0][n]), "+v"(acc[ai][bj][1][n]), "+v"(acc[ai][bj][2][n]), "+v"(acc[ai][bj][3][n]));
;             asm volatile("" ::: "memory");
; #pragma unroll
;             for (int m = 0; m < 4; ++m) xc[m] = xn[m]; }
	v_pk_mul_f32 v[58:59], v[242:243], v[58:59]
	v_pk_mul_f32 v[56:57], v[240:241], v[56:57]
	v_pk_mul_f32 v[38:39], v[242:243], v[38:39]
	v_pk_mul_f32 v[36:37], v[240:241], v[36:37]
	v_pk_mul_f32 v[14:15], v[242:243], v[14:15]
	v_pk_mul_f32 v[12:13], v[240:241], v[12:13]
	v_pk_mul_f32 v[2:3], v[242:243], v[2:3]
	v_pk_mul_f32 v[0:1], v[240:241], v[0:1]
	v_pk_fma_f32 v[58:59], v[210:211], s[34:35], v[58:59] op_sel_hi:[1,0,1]
	v_pk_fma_f32 v[56:57], v[208:209], s[34:35], v[56:57] op_sel_hi:[1,0,1]
	v_pk_fma_f32 v[38:39], v[206:207], s[34:35], v[38:39] op_sel_hi:[1,0,1]
	v_pk_fma_f32 v[36:37], v[204:205], s[34:35], v[36:37] op_sel_hi:[1,0,1]
	v_pk_fma_f32 v[14:15], v[202:203], s[34:35], v[14:15] op_sel_hi:[1,0,1]
	v_pk_fma_f32 v[12:13], v[200:201], s[34:35], v[12:13] op_sel_hi:[1,0,1]
	v_pk_fma_f32 v[2:3], v[198:199], s[34:35], v[2:3] op_sel_hi:[1,0,1]
	v_pk_fma_f32 v[0:1], v[196:197], s[34:35], v[0:1] op_sel_hi:[1,0,1]
	v_add_u32_e32 v198, 64, v166
	s_nop 0
	global_load_dwordx4 v[164:167], v[164:165], off offset:576 nt
	s_nop 0
	global_load_dwordx4 v[184:187], v[162:163], off offset:576 nt
	s_nop 0
	global_load_dwordx4 v[160:163], v[160:161], off offset:576 nt
	s_nop 0
	global_load_dwordx4 v[188:191], v[158:159], off offset:576 nt
	v_mov_b32_e32 v196, v80
	v_mov_b32_e32 v197, v83
	v_cmp_lt_i32_e32 vcc, v148, v198
	s_waitcnt vmcnt(4)
	v_pk_add_f32 v[118:119], v[118:119], v[230:231]
	v_pk_add_f32 v[116:117], v[116:117], v[228:229]
	v_pk_add_f32 v[110:111], v[110:111], v[230:231]
	v_pk_add_f32 v[108:109], v[108:109], v[228:229]
	v_pk_add_f32 v[102:103], v[102:103], v[230:231]
	v_pk_add_f32 v[100:101], v[100:101], v[228:229]
	v_pk_add_f32 v[98:99], v[98:99], v[230:231]
	v_pk_add_f32 v[96:97], v[96:97], v[228:229]
	s_waitcnt vmcnt(4)
	v_pk_mul_f32 v[118:119], v[246:247], v[118:119]
	v_pk_mul_f32 v[116:117], v[244:245], v[116:117]
	v_pk_mul_f32 v[110:111], v[246:247], v[110:111]
	v_pk_mul_f32 v[108:109], v[244:245], v[108:109]
	v_pk_mul_f32 v[102:103], v[246:247], v[102:103]
	v_pk_mul_f32 v[100:101], v[244:245], v[100:101]
	v_pk_mul_f32 v[98:99], v[246:247], v[98:99]
	v_pk_mul_f32 v[96:97], v[244:245], v[96:97]
	v_pk_fma_f32 v[118:119], v[142:143], s[34:35], v[118:119] op_sel_hi:[1,0,1]
	v_pk_fma_f32 v[116:117], v[140:141], s[34:35], v[116:117] op_sel_hi:[1,0,1]
	v_pk_fma_f32 v[110:111], v[138:139], s[34:35], v[110:111] op_sel_hi:[1,0,1]
	v_pk_fma_f32 v[108:109], v[136:137], s[34:35], v[108:109] op_sel_hi:[1,0,1]
	v_pk_fma_f32 v[102:103], v[134:135], s[34:35], v[102:103] op_sel_hi:[1,0,1]
	v_pk_fma_f32 v[100:101], v[132:133], s[34:35], v[100:101] op_sel_hi:[1,0,1]
	v_pk_fma_f32 v[98:99], v[130:131], s[34:35], v[98:99] op_sel_hi:[1,0,1]
	v_pk_fma_f32 v[96:97], v[128:129], s[34:35], v[96:97] op_sel_hi:[1,0,1]
	v_mov_b32_e32 v130, v85
	v_mov_b32_e32 v131, v86
	v_mov_b32_e32 v132, v84
	v_mov_b32_e32 v133, v87
	v_pk_add_f32 v[128:129], v[194:195], v[196:197]
	v_pk_add_f32 v[130:131], v[130:131], v[132:133]
	v_add_f32_e32 v128, v128, v129
	v_pk_add_f32 v[130:131], v[130:131], v[130:131] op_sel:[0,1] op_sel_hi:[1,0]
	v_add_f32_e32 v128, 0, v128
	v_add_f32_e32 v132, v72, v73
	v_add_f32_e32 v142, v74, v75
	v_mov_b32_e32 v129, v116
	v_mov_b32_e32 v131, v117
	v_mov_b32_e32 v133, v118
	v_mov_b32_e32 v143, v119
	v_pk_add_f32 v[128:129], v[128:129], v[130:131]
	v_pk_add_f32 v[130:131], v[132:133], v[142:143]
	v_cndmask_b32_e32 v148, v172, v148, vcc
	v_pk_add_f32 v[128:129], v[128:129], v[130:131]
	v_lshlrev_b32_e32 v148, 2, v148
	v_add_f32_e32 v129, v128, v129
	v_mov_b32_e32 v130, v129
	v_mov_b32_e32 v212, v129
	s_nop 1
	v_permlane16_swap_b32_e32 v130, v212
	v_xor_b32_e32 v128, 32, v172
	v_cmp_lt_i32_e32 vcc, v128, v198
	s_waitcnt lgkmcnt(0)
;     __device__ __forceinline__ bool run(const f32x4 (&v)[2][2][4][2], const Unit& u, int wr, int wc, int fr, int fq, PG8_LAS unsigned char* lds, int wid, int lane) const {
;     ...
;                     for (int n = 0; n < 2; ++n) { const f32x4 x = v[ai][bj][m][n]; s += (x[0] + x[1]) + (x[2] + x[3]); }
;                 s += __shfl_xor(s, 16); s += __shfl_xor(s, 32);
;                 const float mw = s * (1.0f / 64.0f); float q = 0.f;
; #pragma unroll
;                 for (int bj = 0; bj < 2; ++bj)
; #pragma unroll
;                     for (int n = 0; n < 2; ++n) { const f32x4 d = v[ai][bj][m][n] - mw; q += (d[0] * d[0] + d[1] * d[1]) + (d[2] * d[2] + d[3] * d[3]); }
;                 q += __shfl_xor(q, 16); q += __shfl_xor(q, 32);
;                 if (fq == 0) P[(ai * HALF + wr * 64 + m * 16 + fr) * 4 + wc] = (f32x2v){mw, q};
;     __device__ __forceinline__ void fused(f32x4 (&acc)[2][2][4][2], const Unit& u, int wr, int wc, int fr, int fq, PG8_LAS unsigned char* lds, int wid, int lane) const {
;     ...
;             for (int m = 0; m < 4; ++m) acc[ai][bj][m][n] = xc[m] * ALPHA + gv * (acc[ai][bj][m][n] + bv);
;             asm volatile("" : "+v"(acc[ai][bj][0][n]), "+v"(acc[ai][bj][1][n]), "+v"(acc[ai][bj][2][n]), "+v"(acc[ai][bj][3][n]));
	v_add_f32_e32 v129, v130, v212
	v_cndmask_b32_e32 v128, v172, v128, vcc
	v_lshlrev_b32_e32 v128, 2, v128
	v_mov_b32_e32 v130, v129
	v_mov_b32_e32 v212, v129
	s_nop 1
	v_permlane32_swap_b32_e32 v130, v212
	s_waitcnt lgkmcnt(0)
	v_add_f32_e32 v129, v130, v212
	v_fmamk_f32 v131, v129, 0xbc800000, v83
	v_fmamk_f32 v133, v129, 0xbc800000, v81
	v_fmamk_f32 v143, v129, 0xbc800000, v87
	v_fmamk_f32 v157, v129, 0xbc800000, v85
	v_fmamk_f32 v130, v129, 0xbc800000, v82
	v_fmamk_f32 v132, v129, 0xbc800000, v80
	v_fmamk_f32 v142, v129, 0xbc800000, v86
	v_fmamk_f32 v156, v129, 0xbc800000, v84
	v_fmamk_f32 v159, v129, 0xbc800000, v75
	v_fmamk_f32 v177, v129, 0xbc800000, v73
	v_mul_f32_e32 v133, v133, v133
	v_mul_f32_e32 v131, v131, v131
	v_mul_f32_e32 v157, v157, v157
	v_mul_f32_e32 v143, v143, v143
	v_fmamk_f32 v158, v129, 0xbc800000, v74
	v_fmamk_f32 v176, v129, 0xbc800000, v72
	v_fmamk_f32 v179, v129, 0xbc800000, v119
	v_fmamk_f32 v181, v129, 0xbc800000, v117
	v_mul_f32_e32 v177, v177, v177
	v_mul_f32_e32 v159, v159, v159
	v_fmac_f32_e32 v133, v132, v132
	v_fmac_f32_e32 v131, v130, v130
	v_fmac_f32_e32 v157, v156, v156
	v_fmac_f32_e32 v143, v142, v142
	v_fmamk_f32 v178, v129, 0xbc800000, v118
	v_fmamk_f32 v180, v129, 0xbc800000, v116
	v_mul_f32_e32 v181, v181, v181
	v_mul_f32_e32 v179, v179, v179
	v_fmac_f32_e32 v177, v176, v176
	v_fmac_f32_e32 v159, v158, v158
	v_add_f32_e32 v130, v133, v131
	v_add_f32_e32 v131, v157, v143
	v_fmac_f32_e32 v181, v180, v180
	v_fmac_f32_e32 v179, v178, v178
	v_add_f32_e32 v132, v177, v159
	v_add_f32_e32 v130, v130, v131
	v_add_f32_e32 v133, v181, v179
	v_add_f32_e32 v130, v132, v130
	v_add_f32_e32 v131, v133, v130
	v_mov_b32_e32 v132, v131
	v_mov_b32_e32 v212, v131
	s_nop 1
	v_permlane16_swap_b32_e32 v132, v212
	v_and_b32_e32 v130, 63, v174
	v_cmp_gt_u32_e32 vcc, 16, v130
	s_waitcnt lgkmcnt(0)
	v_add_f32_e32 v131, v132, v212
	s_waitcnt vmcnt(0)
	v_pk_add_f32 v[126:127], v[126:127], v[230:231]
	v_pk_add_f32 v[124:125], v[124:125], v[228:229]
	v_pk_add_f32 v[122:123], v[122:123], v[230:231]
	v_pk_add_f32 v[120:121], v[120:121], v[228:229]
	v_pk_add_f32 v[114:115], v[114:115], v[230:231]
	v_pk_add_f32 v[112:113], v[112:113], v[228:229]
	v_pk_add_f32 v[106:107], v[106:107], v[230:231]
	v_pk_add_f32 v[104:105], v[104:105], v[228:229]
	v_mov_b32_e32 v132, v131
	v_mov_b32_e32 v212, v131
	s_nop 1
	v_permlane32_swap_b32_e32 v132, v212
	s_waitcnt vmcnt(0)
	v_pk_mul_f32 v[126:127], v[246:247], v[126:127]
	v_pk_mul_f32 v[124:125], v[244:245], v[124:125]
	v_pk_mul_f32 v[122:123], v[246:247], v[122:123]
	v_pk_mul_f32 v[120:121], v[244:245], v[120:121]
	v_pk_mul_f32 v[114:115], v[246:247], v[114:115]
	v_pk_mul_f32 v[112:113], v[244:245], v[112:113]
	v_pk_mul_f32 v[106:107], v[246:247], v[106:107]
	v_pk_mul_f32 v[104:105], v[244:245], v[104:105]
	v_pk_fma_f32 v[126:127], v[166:167], s[34:35], v[126:127] op_sel_hi:[1,0,1]
	v_pk_fma_f32 v[124:125], v[164:165], s[34:35], v[124:125] op_sel_hi:[1,0,1]
	v_pk_fma_f32 v[122:123], v[186:187], s[34:35], v[122:123] op_sel_hi:[1,0,1]
	v_pk_fma_f32 v[120:121], v[184:185], s[34:35], v[120:121] op_sel_hi:[1,0,1]
	v_pk_fma_f32 v[114:115], v[162:163], s[34:35], v[114:115] op_sel_hi:[1,0,1]
	v_pk_fma_f32 v[112:113], v[160:161], s[34:35], v[112:113] op_sel_hi:[1,0,1]
	v_pk_fma_f32 v[106:107], v[190:191], s[34:35], v[106:107] op_sel_hi:[1,0,1]
	v_pk_fma_f32 v[104:105], v[188:189], s[34:35], v[104:105] op_sel_hi:[1,0,1]
	s_nop 0
	s_and_saveexec_b64 s[0:1], vcc
	s_cbranch_execz .LBB0_498
	s_lshl_b32 s39, s59, 11
	s_add_i32 s39, s7, s39
	v_mul_f32_e32 v134, 0x3c800000, v129
	v_lshl_add_u32 v129, v175, 5, s39
	s_waitcnt lgkmcnt(0)
	v_add_f32_e32 v135, v132, v212
	ds_write_b64 v129, v[134:135]
